# scan loaders: staging writes start ~640 cycles after the chunk barrier (s_sleep) so they miss the scanners' first operand reads
# baseline (speedup 1.0000x reference)
.Lyred_first:
	s_sleep 10
	s_cmp_eq_u32 s34, 0x379000
	s_cbranch_scc1 .LBB0_823
	s_andn2_b32 s0, 1, s54
	s_mul_i32 s0, s0, 0xc000
	s_add_i32 s4, s0, 0
	v_add_u32_e32 v28, s4, v103
	s_and_saveexec_b64 s[0:1], s[10:11]
	s_xor_b64 s[44:45], exec, s[0:1]
	s_cbranch_execz .LBB0_795
	v_lshl_add_u32 v28, v104, 2, v28
	v_add3_u32 v36, v28, v127, s53
	s_waitcnt vmcnt(6)
	s_mov_b32 vcc_lo, 0xaaaaaaaa
	s_mov_b32 vcc_hi, 0xaaaaaaaa
	v_cndmask_b32_e32 v37, v2, v0, vcc
	v_cndmask_b32_e32 v38, v3, v1, vcc
	v_add_u32_e32 v40, -16, v36
	v_cndmask_b32_e32 v36, v36, v40, vcc
	v_mov_b32_dpp v41, v37 quad_perm:[1,0,3,2] row_mask:0xf bank_mask:0xf bound_ctrl:1
	v_mov_b32_dpp v42, v38 quad_perm:[1,0,3,2] row_mask:0xf bank_mask:0xf bound_ctrl:1
	v_cndmask_b32_e32 v37, v0, v41, vcc
	v_cndmask_b32_e32 v38, v1, v42, vcc
	v_cndmask_b32_e32 v41, v41, v2, vcc
	v_cndmask_b32_e32 v42, v42, v3, vcc
	v_lshlrev_b32_e32 v28, 16, v37
	v_and_b32_e32 v29, 0xffff0000, v37
	v_lshlrev_b32_e32 v30, 16, v38
	v_and_b32_e32 v31, 0xffff0000, v38
	ds_write_b128 v36, v[28:31]
	v_lshlrev_b32_e32 v28, 16, v41
	v_and_b32_e32 v29, 0xffff0000, v41
	v_lshlrev_b32_e32 v30, 16, v42
	v_and_b32_e32 v31, 0xffff0000, v42
	ds_write_b128 v36, v[28:31] offset:32
